# chunk attention online softmax: 32 score-max subtractions as 16 in-place packed subtracts, 32-term row sum as 14 packed adds + 3 adds (pairwise association), exps unchanged
# baseline (speedup 1.0000x reference)
; #define MFMA(a, b, c) __builtin_amdgcn_mfma_f32_32x32x16_bf16((a), (b), (c), 0, 0, 0)
; DI unsigned pack2(float a, float b) { const f32x2 v = {a, b}; return __builtin_bit_cast(unsigned, __builtin_convertvector(v, bf16v2)); }
; DI void attn_item(const Params& p, char* lds, int item) {
;     ...
;       mx = fmaxf(mx, __shfl_xor(mx, 32));
;       const float mnew = fmaxf(mrun, mx);
;       const float alpha = __builtin_amdgcn_exp2f(mrun - mnew);
;       mrun = mnew;
;       float ps = 0.f;
; #pragma unroll
;       for (int sub = 0; sub < 2; ++sub)
; #pragma unroll
;         for (int r = 0; r < 16; ++r) { const float e = __builtin_amdgcn_exp2f(S[sub][r] - mnew); S[sub][r] = e; ps += e; }
;       lrun = lrun * alpha + ps;
; #pragma unroll
;       for (int r = 0; r < 16; ++r) { O[0][r] *= alpha; O[1][r] *= alpha; }
; #pragma unroll
;       for (int sub = 0; sub < 2; ++sub) {
;         bf16x8 Pf[2];
; #pragma unroll
;         for (int ks = 0; ks < 2; ++ks) {
;           union { bf16x8 v; unsigned u[4]; } cv;
;           for (int j2 = 0; j2 < 4; ++j2) cv.u[j2] = pack2(S[sub][8 * ks + 2 * j2], S[sub][8 * ks + 2 * j2 + 1]);
;           Pf[ks] = cv.v;
;         }
;         const u16* vl = Vl + cur * 64 * 72 + l31 * 72 + sub * 32 + 8 * hh;
; #pragma unroll
;         for (int dt = 0; dt < 2; ++dt)
; #pragma unroll
;           for (int ks = 0; ks < 2; ++ks) O[dt] = MFMA(ldfrag(vl + dt * 32 * 72 + 16 * ks), Pf[ks], O[dt]);
;       }
.LBB0_372:
	s_or_b64 exec, exec, s[16:17]
	s_nop 5
	v_and_b32_e32 v49, 64, v114
	v_xor_b32_e32 v48, 32, v114
	v_add_u32_e32 v49, 64, v49
	v_cmp_lt_i32_e32 vcc, v48, v49
	s_nop 1
	v_cndmask_b32_e32 v48, v114, v48, vcc
	v_lshlrev_b32_e32 v48, 2, v48
	ds_bpermute_b32 v48, v48, v0
	s_waitcnt lgkmcnt(0)
	v_max3_f32 v48, v138, v0, v48
	v_pk_add_f32 v[92:93], v[92:93], v[48:49] op_sel_hi:[1,0] neg_lo:[0,1] neg_hi:[0,1]
	v_exp_f32_e32 v49, v92
	v_exp_f32_e32 v51, v93
	v_pk_add_f32 v[88:89], v[88:89], v[48:49] op_sel_hi:[1,0] neg_lo:[0,1] neg_hi:[0,1]
	v_exp_f32_e32 v52, v88
	v_exp_f32_e32 v53, v89
	v_pk_add_f32 v[12:13], v[12:13], v[48:49] op_sel_hi:[1,0] neg_lo:[0,1] neg_hi:[0,1]
	v_exp_f32_e32 v54, v12
	v_exp_f32_e32 v50, v13
	v_pk_add_f32 v[10:11], v[10:11], v[48:49] op_sel_hi:[1,0] neg_lo:[0,1] neg_hi:[0,1]
	v_exp_f32_e32 v55, v10
	v_exp_f32_e32 v11, v11
	v_pk_add_f32 v[96:97], v[96:97], v[48:49] op_sel_hi:[1,0] neg_lo:[0,1] neg_hi:[0,1]
	v_exp_f32_e32 v56, v96
	v_exp_f32_e32 v57, v97
	v_pk_add_f32 v[94:95], v[94:95], v[48:49] op_sel_hi:[1,0] neg_lo:[0,1] neg_hi:[0,1]
	v_exp_f32_e32 v58, v94
	v_exp_f32_e32 v59, v95
	v_pk_add_f32 v[90:91], v[90:91], v[48:49] op_sel_hi:[1,0] neg_lo:[0,1] neg_hi:[0,1]
	v_exp_f32_e32 v60, v90
	v_exp_f32_e32 v61, v91
	v_pk_add_f32 v[14:15], v[14:15], v[48:49] op_sel_hi:[1,0] neg_lo:[0,1] neg_hi:[0,1]
	v_exp_f32_e32 v62, v14
	v_exp_f32_e32 v63, v15
	v_pk_add_f32 v[98:99], v[98:99], v[48:49] op_sel_hi:[1,0] neg_lo:[0,1] neg_hi:[0,1]
	v_exp_f32_e32 v88, v98
	v_exp_f32_e32 v89, v99
	v_pk_add_f32 v[100:101], v[100:101], v[48:49] op_sel_hi:[1,0] neg_lo:[0,1] neg_hi:[0,1]
	v_exp_f32_e32 v90, v100
	v_exp_f32_e32 v91, v101
	v_pk_add_f32 v[102:103], v[102:103], v[48:49] op_sel_hi:[1,0] neg_lo:[0,1] neg_hi:[0,1]
	v_exp_f32_e32 v92, v102
	v_exp_f32_e32 v93, v103
	v_pk_add_f32 v[104:105], v[104:105], v[48:49] op_sel_hi:[1,0] neg_lo:[0,1] neg_hi:[0,1]
	v_exp_f32_e32 v94, v104
	v_exp_f32_e32 v95, v105
	v_pk_add_f32 v[106:107], v[106:107], v[48:49] op_sel_hi:[1,0] neg_lo:[0,1] neg_hi:[0,1]
	v_exp_f32_e32 v96, v106
	v_exp_f32_e32 v97, v107
	v_pk_add_f32 v[108:109], v[108:109], v[48:49] op_sel_hi:[1,0] neg_lo:[0,1] neg_hi:[0,1]
	v_exp_f32_e32 v98, v108
	v_exp_f32_e32 v99, v109
	v_pk_add_f32 v[110:111], v[110:111], v[48:49] op_sel_hi:[1,0] neg_lo:[0,1] neg_hi:[0,1]
	v_exp_f32_e32 v100, v110
	v_exp_f32_e32 v101, v111
	v_pk_add_f32 v[112:113], v[112:113], v[48:49] op_sel_hi:[1,0] neg_lo:[0,1] neg_hi:[0,1]
	v_exp_f32_e32 v102, v112
	v_exp_f32_e32 v103, v113
	v_sub_f32_e32 v0, v138, v48
	v_exp_f32_e32 v0, v0
	v_add_u32_e32 v104, s30, v133
	v_pk_add_f32 v[140:141], v[50:51], v[52:53]
	v_pk_add_f32 v[140:141], v[140:141], v[54:55]
	v_pk_add_f32 v[140:141], v[140:141], v[56:57]
	v_pk_add_f32 v[140:141], v[140:141], v[58:59]
	v_pk_add_f32 v[140:141], v[140:141], v[60:61]
	v_pk_add_f32 v[140:141], v[140:141], v[62:63]
	v_pk_add_f32 v[140:141], v[140:141], v[88:89]
	v_pk_add_f32 v[140:141], v[140:141], v[90:91]
	v_pk_add_f32 v[140:141], v[140:141], v[92:93]
	v_pk_add_f32 v[140:141], v[140:141], v[94:95]
	v_pk_add_f32 v[140:141], v[140:141], v[96:97]
	v_pk_add_f32 v[140:141], v[140:141], v[98:99]
	v_pk_add_f32 v[140:141], v[140:141], v[100:101]
	v_pk_add_f32 v[140:141], v[140:141], v[102:103]
	v_add_f32_e32 v10, v140, v141
	v_add_f32_e32 v10, v49, v10
	v_add_f32_e32 v10, v11, v10
	v_cvt_pk_bf16_f32 v12, v49, v51
	v_cvt_pk_bf16_f32 v13, v52, v53
	v_cvt_pk_bf16_f32 v14, v54, v50
	v_cvt_pk_bf16_f32 v15, v55, v11
	v_cvt_pk_bf16_f32 v50, v56, v57
	v_cvt_pk_bf16_f32 v51, v58, v59
	v_cvt_pk_bf16_f32 v52, v60, v61
	ds_read_b128 v[54:57], v104 offset:18432
	ds_read_b128 v[58:61], v104 offset:18464
	v_pk_mul_f32 v[46:47], v[46:47], v[0:1] op_sel_hi:[1,0]
	v_pk_mul_f32 v[44:45], v[44:45], v[0:1] op_sel_hi:[1,0]
	v_pk_mul_f32 v[42:43], v[42:43], v[0:1] op_sel_hi:[1,0]
	v_pk_mul_f32 v[40:41], v[40:41], v[0:1] op_sel_hi:[1,0]
	v_pk_mul_f32 v[38:39], v[38:39], v[0:1] op_sel_hi:[1,0]
	v_pk_mul_f32 v[36:37], v[36:37], v[0:1] op_sel_hi:[1,0]
	v_pk_mul_f32 v[34:35], v[34:35], v[0:1] op_sel_hi:[1,0]
	v_pk_mul_f32 v[32:33], v[32:33], v[0:1] op_sel_hi:[1,0]
	v_pk_mul_f32 v[30:31], v[30:31], v[0:1] op_sel_hi:[1,0]
	v_pk_mul_f32 v[28:29], v[28:29], v[0:1] op_sel_hi:[1,0]
	s_waitcnt lgkmcnt(1)
	v_mfma_f32_32x32x16_bf16 v[32:47], v[54:57], v[12:15], v[32:47]
	ds_read_b128 v[54:57], v104 offset:23040
	v_mul_f32_e64 v26, v26, v0
	v_mul_f32_e64 v27, v27, v0
	v_mul_f32_e64 v24, v24, v0
	v_mul_f32_e64 v25, v25, v0
	v_pk_mul_f32 v[22:23], v[22:23], v[0:1] op_sel_hi:[1,0]
	v_pk_mul_f32 v[20:21], v[20:21], v[0:1] op_sel_hi:[1,0]
	v_pk_mul_f32 v[18:19], v[18:19], v[0:1] op_sel_hi:[1,0]
	v_pk_mul_f32 v[16:17], v[16:17], v[0:1] op_sel_hi:[1,0]
	v_cvt_pk_bf16_f32 v53, v62, v63
	s_waitcnt lgkmcnt(0)
	v_mfma_f32_32x32x16_bf16 v[16:31], v[54:57], v[12:15], v[16:31]
	ds_read_b128 v[12:15], v104 offset:23072
	ds_read_b128 v[54:57], v104 offset:18496
	v_mfma_f32_32x32x16_bf16 v[32:47], v[58:61], v[50:53], v[32:47]
	s_waitcnt lgkmcnt(1)
	v_mfma_f32_32x32x16_bf16 v[16:31], v[12:15], v[50:53], v[16:31]
	v_cvt_pk_bf16_f32 v12, v88, v89
	v_cvt_pk_bf16_f32 v13, v90, v91
	v_cvt_pk_bf16_f32 v14, v92, v93
	v_cvt_pk_bf16_f32 v15, v94, v95
	v_cvt_pk_bf16_f32 v50, v96, v97
	v_cvt_pk_bf16_f32 v51, v98, v99
	v_cvt_pk_bf16_f32 v52, v100, v101
	s_waitcnt lgkmcnt(0)
	v_mfma_f32_32x32x16_bf16 v[32:47], v[54:57], v[12:15], v[32:47]
	ds_read_b128 v[54:57], v104 offset:18528
	v_cvt_pk_bf16_f32 v53, v102, v103
	s_waitcnt lgkmcnt(0)
	v_mfma_f32_32x32x16_bf16 v[32:47], v[54:57], v[50:53], v[32:47]
	ds_read_b128 v[54:57], v104 offset:23104
	v_fmac_f32_e32 v10, v137, v0
	v_mov_b32_e32 v138, v48
	v_mov_b32_e32 v137, v10
	s_waitcnt lgkmcnt(0)
	v_mfma_f32_32x32x16_bf16 v[16:31], v[54:57], v[12:15], v[16:31]
	ds_read_b128 v[12:15], v104 offset:23136
	s_waitcnt lgkmcnt(0)
	v_mfma_f32_32x32x16_bf16 v[16:31], v[12:15], v[50:53], v[16:31]
